# scan consumer: packed ops grouped, only LDS ops between the DPP adds (even steps too); nt row loads kept
# baseline (speedup 1.0000x reference)
.Lscan_chunk:
	s_waitcnt lgkmcnt(5)
	v_pk_mul_f32 v[0:1], v[58:59], v[0:1] op_sel_hi:[0,1]
	v_pk_fma_f32 v[0:1], v[58:59], v[2:3], v[0:1] op_sel:[1,0,0] op_sel_hi:[1,1,1]
	v_pk_fma_f32 v[0:1], v[60:61], v[16:17], v[0:1] op_sel_hi:[0,1,1]
	v_pk_fma_f32 v[0:1], v[60:61], v[18:19], v[0:1] op_sel:[1,0,0] op_sel_hi:[1,1,1]
	v_pk_fma_f32 v[12:13], v[58:59], v[4:5], v[12:13]
	v_pk_fma_f32 v[14:15], v[60:61], v[6:7], v[14:15]
	v_add_f32_dpp v0, v0, v0 quad_perm:[1,0,3,2] row_mask:0xf bank_mask:0xf bound_ctrl:1
	ds_write2st64_b32 v72, v81, v1 offset0:28 offset1:30
	v_mov_b32_e32 v72, v67
	ds_read_b128 v[80:83], v74 offset:9216
	v_add_f32_dpp v0, v0, v0 quad_perm:[2,3,0,1] row_mask:0xf bank_mask:0xf bound_ctrl:1
	ds_read_b128 v[96:99], v74 offset:9472
	ds_read_b128 v[84:87], v74 offset:9728
	v_add_f32_dpp v0, v0, v0 row_half_mirror row_mask:0xf bank_mask:0xf bound_ctrl:1
	ds_read_b128 v[92:95], v75 offset:9216
	ds_read_b128 v[88:91], v74 offset:9984
	v_add_f32_dpp v0, v0, v0 row_mirror row_mask:0xf bank_mask:0xf bound_ctrl:1
	v_pk_fma_f32 v[58:59], v[8:9], v[0:1], v[12:13] op_sel_hi:[1,0,1]
	v_pk_fma_f32 v[60:61], v[10:11], v[0:1], v[14:15] op_sel_hi:[1,0,1]
	ds_read_b128 v[0:3], v74 offset:12288
	v_pk_mul_f32 v[20:21], v[58:59], v[20:21] op_sel_hi:[0,1]
	v_pk_fma_f32 v[20:21], v[58:59], v[22:23], v[20:21] op_sel:[1,0,0] op_sel_hi:[1,1,1]
	v_pk_fma_f32 v[20:21], v[60:61], v[36:37], v[20:21] op_sel_hi:[0,1,1]
	v_pk_fma_f32 v[20:21], v[60:61], v[38:39], v[20:21] op_sel:[1,0,0] op_sel_hi:[1,1,1]
	v_pk_fma_f32 v[32:33], v[58:59], v[24:25], v[32:33]
	v_pk_fma_f32 v[34:35], v[60:61], v[26:27], v[34:35]
	v_add_f32_dpp v20, v20, v20 quad_perm:[1,0,3,2] row_mask:0xf bank_mask:0xf bound_ctrl:1
	ds_read_b128 v[16:19], v74 offset:12544
	ds_read_b128 v[4:7], v74 offset:12800
	v_add_f32_dpp v20, v20, v20 quad_perm:[2,3,0,1] row_mask:0xf bank_mask:0xf bound_ctrl:1
	ds_read_b128 v[12:15], v75 offset:12288
	ds_read_b128 v[8:11], v74 offset:13056
	v_add_f32_dpp v20, v20, v20 row_half_mirror row_mask:0xf bank_mask:0xf bound_ctrl:1
	s_nop 1
	v_add_f32_dpp v20, v20, v20 row_mirror row_mask:0xf bank_mask:0xf bound_ctrl:1
	v_pk_fma_f32 v[58:59], v[28:29], v[20:21], v[32:33] op_sel_hi:[1,0,1]
	v_pk_fma_f32 v[60:61], v[30:31], v[20:21], v[34:35] op_sel_hi:[1,0,1]
	s_waitcnt lgkmcnt(5)
	v_pk_mul_f32 v[46:47], v[58:59], v[46:47] op_sel_hi:[0,1]
	v_pk_fma_f32 v[46:47], v[58:59], v[48:49], v[46:47] op_sel:[1,0,0] op_sel_hi:[1,1,1]
	v_pk_fma_f32 v[46:47], v[60:61], v[76:77], v[46:47] op_sel_hi:[0,1,1]
	v_pk_fma_f32 v[46:47], v[60:61], v[78:79], v[46:47] op_sel:[1,0,0] op_sel_hi:[1,1,1]
	v_pk_fma_f32 v[68:69], v[58:59], v[50:51], v[68:69]
	v_pk_fma_f32 v[70:71], v[60:61], v[52:53], v[70:71]
	v_add_f32_dpp v46, v46, v46 quad_perm:[1,0,3,2] row_mask:0xf bank_mask:0xf bound_ctrl:1
	ds_write2st64_b32 v72, v21, v47 offset0:0 offset1:2
	ds_read_b128 v[20:23], v74 offset:15360
	v_add_f32_dpp v46, v46, v46 quad_perm:[2,3,0,1] row_mask:0xf bank_mask:0xf bound_ctrl:1
	ds_read_b128 v[36:39], v74 offset:15616
	ds_read_b128 v[24:27], v74 offset:15872
	v_add_f32_dpp v46, v46, v46 row_half_mirror row_mask:0xf bank_mask:0xf bound_ctrl:1
	ds_read_b128 v[32:35], v75 offset:15360
	ds_read_b128 v[28:31], v74 offset:16128
	v_add_f32_dpp v46, v46, v46 row_mirror row_mask:0xf bank_mask:0xf bound_ctrl:1
	v_pk_fma_f32 v[58:59], v[54:55], v[46:47], v[68:69] op_sel_hi:[1,0,1]
	v_pk_fma_f32 v[60:61], v[56:57], v[46:47], v[70:71] op_sel_hi:[1,0,1]
	ds_read_b128 v[46:49], v74 offset:18432
	v_pk_mul_f32 v[80:81], v[58:59], v[80:81] op_sel_hi:[0,1]
	v_pk_fma_f32 v[80:81], v[58:59], v[82:83], v[80:81] op_sel:[1,0,0] op_sel_hi:[1,1,1]
	v_pk_fma_f32 v[80:81], v[60:61], v[96:97], v[80:81] op_sel_hi:[0,1,1]
	v_pk_fma_f32 v[80:81], v[60:61], v[98:99], v[80:81] op_sel:[1,0,0] op_sel_hi:[1,1,1]
	v_pk_fma_f32 v[92:93], v[58:59], v[84:85], v[92:93]
	v_pk_fma_f32 v[94:95], v[60:61], v[86:87], v[94:95]
	v_add_f32_dpp v80, v80, v80 quad_perm:[1,0,3,2] row_mask:0xf bank_mask:0xf bound_ctrl:1
	ds_read_b128 v[76:79], v74 offset:18688
	ds_read_b128 v[50:53], v74 offset:18944
	v_add_f32_dpp v80, v80, v80 quad_perm:[2,3,0,1] row_mask:0xf bank_mask:0xf bound_ctrl:1
	ds_read_b128 v[68:71], v75 offset:18432
	ds_read_b128 v[54:57], v74 offset:19200
	v_add_f32_dpp v80, v80, v80 row_half_mirror row_mask:0xf bank_mask:0xf bound_ctrl:1
	s_nop 1
	v_add_f32_dpp v80, v80, v80 row_mirror row_mask:0xf bank_mask:0xf bound_ctrl:1
	v_pk_fma_f32 v[58:59], v[88:89], v[80:81], v[92:93] op_sel_hi:[1,0,1]
	v_pk_fma_f32 v[60:61], v[90:91], v[80:81], v[94:95] op_sel_hi:[1,0,1]
	s_waitcnt lgkmcnt(5)
	v_pk_mul_f32 v[0:1], v[58:59], v[0:1] op_sel_hi:[0,1]
	v_pk_fma_f32 v[0:1], v[58:59], v[2:3], v[0:1] op_sel:[1,0,0] op_sel_hi:[1,1,1]
	v_pk_fma_f32 v[0:1], v[60:61], v[16:17], v[0:1] op_sel_hi:[0,1,1]
	v_pk_fma_f32 v[0:1], v[60:61], v[18:19], v[0:1] op_sel:[1,0,0] op_sel_hi:[1,1,1]
	v_pk_fma_f32 v[12:13], v[58:59], v[4:5], v[12:13]
	v_pk_fma_f32 v[14:15], v[60:61], v[6:7], v[14:15]
	v_add_f32_dpp v0, v0, v0 quad_perm:[1,0,3,2] row_mask:0xf bank_mask:0xf bound_ctrl:1
	ds_write2st64_b32 v72, v81, v1 offset0:4 offset1:6
	ds_read_b128 v[80:83], v74 offset:21504
	v_add_f32_dpp v0, v0, v0 quad_perm:[2,3,0,1] row_mask:0xf bank_mask:0xf bound_ctrl:1
	ds_read_b128 v[96:99], v74 offset:21760
	ds_read_b128 v[84:87], v74 offset:22016
	v_add_f32_dpp v0, v0, v0 row_half_mirror row_mask:0xf bank_mask:0xf bound_ctrl:1
	ds_read_b128 v[92:95], v75 offset:21504
	ds_read_b128 v[88:91], v74 offset:22272
	v_add_f32_dpp v0, v0, v0 row_mirror row_mask:0xf bank_mask:0xf bound_ctrl:1
	v_pk_fma_f32 v[58:59], v[8:9], v[0:1], v[12:13] op_sel_hi:[1,0,1]
	v_pk_fma_f32 v[60:61], v[10:11], v[0:1], v[14:15] op_sel_hi:[1,0,1]
	ds_read_b128 v[0:3], v74 offset:24576
	v_pk_mul_f32 v[20:21], v[58:59], v[20:21] op_sel_hi:[0,1]
	v_pk_fma_f32 v[20:21], v[58:59], v[22:23], v[20:21] op_sel:[1,0,0] op_sel_hi:[1,1,1]
	v_pk_fma_f32 v[20:21], v[60:61], v[36:37], v[20:21] op_sel_hi:[0,1,1]
	v_pk_fma_f32 v[20:21], v[60:61], v[38:39], v[20:21] op_sel:[1,0,0] op_sel_hi:[1,1,1]
	v_pk_fma_f32 v[32:33], v[58:59], v[24:25], v[32:33]
	v_pk_fma_f32 v[34:35], v[60:61], v[26:27], v[34:35]
	v_add_f32_dpp v20, v20, v20 quad_perm:[1,0,3,2] row_mask:0xf bank_mask:0xf bound_ctrl:1
	ds_read_b128 v[16:19], v74 offset:24832
	ds_read_b128 v[4:7], v74 offset:25088
	v_add_f32_dpp v20, v20, v20 quad_perm:[2,3,0,1] row_mask:0xf bank_mask:0xf bound_ctrl:1
	ds_read_b128 v[12:15], v75 offset:24576
	ds_read_b128 v[8:11], v74 offset:25344
	v_add_f32_dpp v20, v20, v20 row_half_mirror row_mask:0xf bank_mask:0xf bound_ctrl:1
	s_nop 1
	v_add_f32_dpp v20, v20, v20 row_mirror row_mask:0xf bank_mask:0xf bound_ctrl:1
	v_pk_fma_f32 v[58:59], v[28:29], v[20:21], v[32:33] op_sel_hi:[1,0,1]
	v_pk_fma_f32 v[60:61], v[30:31], v[20:21], v[34:35] op_sel_hi:[1,0,1]
	s_waitcnt lgkmcnt(5)
	v_pk_mul_f32 v[46:47], v[58:59], v[46:47] op_sel_hi:[0,1]
	v_pk_fma_f32 v[46:47], v[58:59], v[48:49], v[46:47] op_sel:[1,0,0] op_sel_hi:[1,1,1]
	v_pk_fma_f32 v[46:47], v[60:61], v[76:77], v[46:47] op_sel_hi:[0,1,1]
	v_pk_fma_f32 v[46:47], v[60:61], v[78:79], v[46:47] op_sel:[1,0,0] op_sel_hi:[1,1,1]
	v_pk_fma_f32 v[68:69], v[58:59], v[50:51], v[68:69]
	v_pk_fma_f32 v[70:71], v[60:61], v[52:53], v[70:71]
	v_add_f32_dpp v46, v46, v46 quad_perm:[1,0,3,2] row_mask:0xf bank_mask:0xf bound_ctrl:1
	ds_write2st64_b32 v72, v21, v47 offset0:8 offset1:10
	ds_read_b128 v[20:23], v74 offset:27648
	v_add_f32_dpp v46, v46, v46 quad_perm:[2,3,0,1] row_mask:0xf bank_mask:0xf bound_ctrl:1
	ds_read_b128 v[36:39], v74 offset:27904
	ds_read_b128 v[24:27], v74 offset:28160
	v_add_f32_dpp v46, v46, v46 row_half_mirror row_mask:0xf bank_mask:0xf bound_ctrl:1
	ds_read_b128 v[32:35], v75 offset:27648
	ds_read_b128 v[28:31], v74 offset:28416
	v_add_f32_dpp v46, v46, v46 row_mirror row_mask:0xf bank_mask:0xf bound_ctrl:1
	v_pk_fma_f32 v[58:59], v[54:55], v[46:47], v[68:69] op_sel_hi:[1,0,1]
	v_pk_fma_f32 v[60:61], v[56:57], v[46:47], v[70:71] op_sel_hi:[1,0,1]
	ds_read_b128 v[46:49], v74 offset:30720
	v_pk_mul_f32 v[80:81], v[58:59], v[80:81] op_sel_hi:[0,1]
	v_pk_fma_f32 v[80:81], v[58:59], v[82:83], v[80:81] op_sel:[1,0,0] op_sel_hi:[1,1,1]
	v_pk_fma_f32 v[80:81], v[60:61], v[96:97], v[80:81] op_sel_hi:[0,1,1]
	v_pk_fma_f32 v[80:81], v[60:61], v[98:99], v[80:81] op_sel:[1,0,0] op_sel_hi:[1,1,1]
	v_pk_fma_f32 v[92:93], v[58:59], v[84:85], v[92:93]
	v_pk_fma_f32 v[94:95], v[60:61], v[86:87], v[94:95]
	v_add_f32_dpp v80, v80, v80 quad_perm:[1,0,3,2] row_mask:0xf bank_mask:0xf bound_ctrl:1
	ds_read_b128 v[76:79], v74 offset:30976
	ds_read_b128 v[50:53], v74 offset:31232
	v_add_f32_dpp v80, v80, v80 quad_perm:[2,3,0,1] row_mask:0xf bank_mask:0xf bound_ctrl:1
	ds_read_b128 v[68:71], v75 offset:30720
	ds_read_b128 v[54:57], v74 offset:31488
	v_add_f32_dpp v80, v80, v80 row_half_mirror row_mask:0xf bank_mask:0xf bound_ctrl:1
	s_nop 1
	v_add_f32_dpp v80, v80, v80 row_mirror row_mask:0xf bank_mask:0xf bound_ctrl:1
	v_pk_fma_f32 v[58:59], v[88:89], v[80:81], v[92:93] op_sel_hi:[1,0,1]
	v_pk_fma_f32 v[60:61], v[90:91], v[80:81], v[94:95] op_sel_hi:[1,0,1]
	s_waitcnt lgkmcnt(5)
	v_pk_mul_f32 v[0:1], v[58:59], v[0:1] op_sel_hi:[0,1]
	v_pk_fma_f32 v[0:1], v[58:59], v[2:3], v[0:1] op_sel:[1,0,0] op_sel_hi:[1,1,1]
	v_pk_fma_f32 v[0:1], v[60:61], v[16:17], v[0:1] op_sel_hi:[0,1,1]
	v_pk_fma_f32 v[0:1], v[60:61], v[18:19], v[0:1] op_sel:[1,0,0] op_sel_hi:[1,1,1]
	v_pk_fma_f32 v[12:13], v[58:59], v[4:5], v[12:13]
	v_pk_fma_f32 v[14:15], v[60:61], v[6:7], v[14:15]
	v_add_f32_dpp v0, v0, v0 quad_perm:[1,0,3,2] row_mask:0xf bank_mask:0xf bound_ctrl:1
	ds_write2st64_b32 v72, v81, v1 offset0:12 offset1:14
	ds_read_b128 v[80:83], v74 offset:33792
	v_add_f32_dpp v0, v0, v0 quad_perm:[2,3,0,1] row_mask:0xf bank_mask:0xf bound_ctrl:1
	ds_read_b128 v[96:99], v74 offset:34048
	ds_read_b128 v[84:87], v74 offset:34304
	v_add_f32_dpp v0, v0, v0 row_half_mirror row_mask:0xf bank_mask:0xf bound_ctrl:1
	ds_read_b128 v[92:95], v75 offset:33792
	ds_read_b128 v[88:91], v74 offset:34560
	v_add_f32_dpp v0, v0, v0 row_mirror row_mask:0xf bank_mask:0xf bound_ctrl:1
	v_pk_fma_f32 v[58:59], v[8:9], v[0:1], v[12:13] op_sel_hi:[1,0,1]
	v_pk_fma_f32 v[60:61], v[10:11], v[0:1], v[14:15] op_sel_hi:[1,0,1]
	ds_read_b128 v[0:3], v74 offset:36864
	v_pk_mul_f32 v[20:21], v[58:59], v[20:21] op_sel_hi:[0,1]
	v_pk_fma_f32 v[20:21], v[58:59], v[22:23], v[20:21] op_sel:[1,0,0] op_sel_hi:[1,1,1]
	v_pk_fma_f32 v[20:21], v[60:61], v[36:37], v[20:21] op_sel_hi:[0,1,1]
	v_pk_fma_f32 v[20:21], v[60:61], v[38:39], v[20:21] op_sel:[1,0,0] op_sel_hi:[1,1,1]
	v_pk_fma_f32 v[32:33], v[58:59], v[24:25], v[32:33]
	v_pk_fma_f32 v[34:35], v[60:61], v[26:27], v[34:35]
	v_add_f32_dpp v20, v20, v20 quad_perm:[1,0,3,2] row_mask:0xf bank_mask:0xf bound_ctrl:1
	ds_read_b128 v[16:19], v74 offset:37120
	ds_read_b128 v[4:7], v74 offset:37376
	v_add_f32_dpp v20, v20, v20 quad_perm:[2,3,0,1] row_mask:0xf bank_mask:0xf bound_ctrl:1
	ds_read_b128 v[12:15], v75 offset:36864
	ds_read_b128 v[8:11], v74 offset:37632
	v_add_f32_dpp v20, v20, v20 row_half_mirror row_mask:0xf bank_mask:0xf bound_ctrl:1
	s_nop 1
	v_add_f32_dpp v20, v20, v20 row_mirror row_mask:0xf bank_mask:0xf bound_ctrl:1
	v_pk_fma_f32 v[58:59], v[28:29], v[20:21], v[32:33] op_sel_hi:[1,0,1]
	v_pk_fma_f32 v[60:61], v[30:31], v[20:21], v[34:35] op_sel_hi:[1,0,1]
	s_waitcnt lgkmcnt(5)
; #define LAS __attribute__((address_space(3)))
; #define RW_LDS_WAIT(X) asm volatile("s_waitcnt lgkmcnt(0)" : "+v"(nk##X), "+v"(dd##X), "+v"(bb##X), "+v"(kp##X), "+v"(rr##X), "+v"(vv##X) :: "memory")
; DI void rwkv_scan_phase(int wv, const Params& P, LAS unsigned char* lds) {
;     ...
;                 f32x2 yacc = (f32x2){0.f, 0.f};
;                 unsigned sbt = sba, vbt = vba; LAS float* ybt = yb;
;                 RW_LDS_LOAD(A, 0); RW_LDS_WAIT(A);
; #pragma unroll 1
;                 for (int tt = 0; tt < RW_T; tt += 16) { sbt = sba + (unsigned)tt * 1280u; vbt = vba + (unsigned)tt * 32u; ybt = yb + tt * 128;
;                     RW_LDS_LOAD(B, 1); RW_STEP(A, 0); RW_LDS_WAIT(B);
;                     RW_LDS_LOAD(A, 2); RW_STEP(B, 1); RW_LDS_WAIT(A);
;                     RW_LDS_LOAD(B, 3); RW_STEP(A, 2); RW_LDS_WAIT(B);
;                     RW_LDS_LOAD(A, 4); RW_STEP(B, 3); RW_LDS_WAIT(A);
;                     RW_LDS_LOAD(B, 5); RW_STEP(A, 4); RW_LDS_WAIT(B);
;                     RW_LDS_LOAD(A, 6); RW_STEP(B, 5); RW_LDS_WAIT(A);
;                     RW_LDS_LOAD(B, 7); RW_STEP(A, 6); RW_LDS_WAIT(B);
;                     RW_LDS_LOAD(A, 8); RW_STEP(B, 7); RW_LDS_WAIT(A);
;                     RW_LDS_LOAD(B, 9); RW_STEP(A, 8); RW_LDS_WAIT(B);
;                     RW_LDS_LOAD(A, 10); RW_STEP(B, 9); RW_LDS_WAIT(A);
;                     RW_LDS_LOAD(B, 11); RW_STEP(A, 10); RW_LDS_WAIT(B);
;                     RW_LDS_LOAD(A, 12); RW_STEP(B, 11); RW_LDS_WAIT(A);
;                     RW_LDS_LOAD(B, 13); RW_STEP(A, 12); RW_LDS_WAIT(B);
;                     RW_LDS_LOAD(A, 14); RW_STEP(B, 13); RW_LDS_WAIT(A);
;                     RW_LDS_LOAD(B, 15); RW_STEP(A, 14); RW_LDS_WAIT(B);
;                     RW_LDS_LOAD(A, 16); RW_STEP(B, 15); RW_LDS_WAIT(A);
;                 }
	v_pk_mul_f32 v[46:47], v[58:59], v[46:47] op_sel_hi:[0,1]
	v_pk_fma_f32 v[46:47], v[58:59], v[48:49], v[46:47] op_sel:[1,0,0] op_sel_hi:[1,1,1]
	v_pk_fma_f32 v[46:47], v[60:61], v[76:77], v[46:47] op_sel_hi:[0,1,1]
	v_pk_fma_f32 v[46:47], v[60:61], v[78:79], v[46:47] op_sel:[1,0,0] op_sel_hi:[1,1,1]
	v_pk_fma_f32 v[68:69], v[58:59], v[50:51], v[68:69]
	v_pk_fma_f32 v[70:71], v[60:61], v[52:53], v[70:71]
	v_add_f32_dpp v46, v46, v46 quad_perm:[1,0,3,2] row_mask:0xf bank_mask:0xf bound_ctrl:1
	ds_write2st64_b32 v72, v21, v47 offset0:16 offset1:18
	ds_read_b128 v[20:23], v74 offset:39936
	v_add_f32_dpp v46, v46, v46 quad_perm:[2,3,0,1] row_mask:0xf bank_mask:0xf bound_ctrl:1
	ds_read_b128 v[36:39], v74 offset:40192
	ds_read_b128 v[24:27], v74 offset:40448
	v_add_f32_dpp v46, v46, v46 row_half_mirror row_mask:0xf bank_mask:0xf bound_ctrl:1
	ds_read_b128 v[32:35], v75 offset:39936
	ds_read_b128 v[28:31], v74 offset:40704
	v_add_f32_dpp v46, v46, v46 row_mirror row_mask:0xf bank_mask:0xf bound_ctrl:1
	v_pk_fma_f32 v[58:59], v[54:55], v[46:47], v[68:69] op_sel_hi:[1,0,1]
	v_pk_fma_f32 v[60:61], v[56:57], v[46:47], v[70:71] op_sel_hi:[1,0,1]
	ds_read_b128 v[46:49], v74 offset:43008
	v_pk_mul_f32 v[80:81], v[58:59], v[80:81] op_sel_hi:[0,1]
	v_pk_fma_f32 v[80:81], v[58:59], v[82:83], v[80:81] op_sel:[1,0,0] op_sel_hi:[1,1,1]
	v_pk_fma_f32 v[80:81], v[60:61], v[96:97], v[80:81] op_sel_hi:[0,1,1]
	v_pk_fma_f32 v[80:81], v[60:61], v[98:99], v[80:81] op_sel:[1,0,0] op_sel_hi:[1,1,1]
	v_pk_fma_f32 v[92:93], v[58:59], v[84:85], v[92:93]
	v_pk_fma_f32 v[94:95], v[60:61], v[86:87], v[94:95]
	v_add_f32_dpp v80, v80, v80 quad_perm:[1,0,3,2] row_mask:0xf bank_mask:0xf bound_ctrl:1
	ds_read_b128 v[76:79], v74 offset:43264
	ds_read_b128 v[50:53], v74 offset:43520
	v_add_f32_dpp v80, v80, v80 quad_perm:[2,3,0,1] row_mask:0xf bank_mask:0xf bound_ctrl:1
	ds_read_b128 v[68:71], v75 offset:43008
	ds_read_b128 v[54:57], v74 offset:43776
	v_add_f32_dpp v80, v80, v80 row_half_mirror row_mask:0xf bank_mask:0xf bound_ctrl:1
	s_nop 1
	v_add_f32_dpp v80, v80, v80 row_mirror row_mask:0xf bank_mask:0xf bound_ctrl:1
	v_pk_fma_f32 v[58:59], v[88:89], v[80:81], v[92:93] op_sel_hi:[1,0,1]
	v_pk_fma_f32 v[60:61], v[90:91], v[80:81], v[94:95] op_sel_hi:[1,0,1]
	s_waitcnt lgkmcnt(5)
	v_pk_mul_f32 v[0:1], v[58:59], v[0:1] op_sel_hi:[0,1]
	v_pk_fma_f32 v[0:1], v[58:59], v[2:3], v[0:1] op_sel:[1,0,0] op_sel_hi:[1,1,1]
	v_pk_fma_f32 v[0:1], v[60:61], v[16:17], v[0:1] op_sel_hi:[0,1,1]
	v_pk_fma_f32 v[0:1], v[60:61], v[18:19], v[0:1] op_sel:[1,0,0] op_sel_hi:[1,1,1]
	v_pk_fma_f32 v[12:13], v[58:59], v[4:5], v[12:13]
	v_pk_fma_f32 v[14:15], v[60:61], v[6:7], v[14:15]
	v_add_f32_dpp v0, v0, v0 quad_perm:[1,0,3,2] row_mask:0xf bank_mask:0xf bound_ctrl:1
	ds_write2st64_b32 v72, v81, v1 offset0:20 offset1:22
	ds_read_b128 v[80:83], v74 offset:46080
	v_add_f32_dpp v0, v0, v0 quad_perm:[2,3,0,1] row_mask:0xf bank_mask:0xf bound_ctrl:1
	ds_read_b128 v[96:99], v74 offset:46336
	ds_read_b128 v[84:87], v74 offset:46592
	v_add_f32_dpp v0, v0, v0 row_half_mirror row_mask:0xf bank_mask:0xf bound_ctrl:1
	ds_read_b128 v[92:95], v75 offset:46080
	ds_read_b128 v[88:91], v74 offset:46848
	v_add_f32_dpp v0, v0, v0 row_mirror row_mask:0xf bank_mask:0xf bound_ctrl:1
	v_pk_fma_f32 v[58:59], v[8:9], v[0:1], v[12:13] op_sel_hi:[1,0,1]
	v_pk_fma_f32 v[60:61], v[10:11], v[0:1], v[14:15] op_sel_hi:[1,0,1]
	v_pk_mul_f32 v[20:21], v[58:59], v[20:21] op_sel_hi:[0,1]
	v_pk_fma_f32 v[20:21], v[58:59], v[22:23], v[20:21] op_sel:[1,0,0] op_sel_hi:[1,1,1]
	v_pk_fma_f32 v[20:21], v[60:61], v[36:37], v[20:21] op_sel_hi:[0,1,1]
	v_pk_fma_f32 v[20:21], v[60:61], v[38:39], v[20:21] op_sel:[1,0,0] op_sel_hi:[1,1,1]
	v_pk_fma_f32 v[32:33], v[58:59], v[24:25], v[32:33]
	v_pk_fma_f32 v[34:35], v[60:61], v[26:27], v[34:35]
	v_add_f32_dpp v20, v20, v20 quad_perm:[1,0,3,2] row_mask:0xf bank_mask:0xf bound_ctrl:1
	s_add_i32 s47, s47, 1
	s_add_i32 s42, s42, 0x2000
	v_add_f32_dpp v20, v20, v20 quad_perm:[2,3,0,1] row_mask:0xf bank_mask:0xf bound_ctrl:1
	s_cmp_eq_u32 s42, 0x6000
	s_cselect_b32 s42, 0, s42
	v_add_f32_dpp v20, v20, v20 row_half_mirror row_mask:0xf bank_mask:0xf bound_ctrl:1
	v_add_u32_e32 v67, s42, v62
	s_nop 0
	v_add_f32_dpp v20, v20, v20 row_mirror row_mask:0xf bank_mask:0xf bound_ctrl:1
	v_pk_fma_f32 v[58:59], v[28:29], v[20:21], v[32:33] op_sel_hi:[1,0,1]
	v_pk_fma_f32 v[60:61], v[30:31], v[20:21], v[34:35] op_sel_hi:[1,0,1]
	s_waitcnt lgkmcnt(0)
	s_barrier
; #define LAS __attribute__((address_space(3)))
; #define RW_LDS_WAIT(X) asm volatile("s_waitcnt lgkmcnt(0)" : "+v"(nk##X), "+v"(dd##X), "+v"(bb##X), "+v"(kp##X), "+v"(rr##X), "+v"(vv##X) :: "memory")
; DI void rwkv_scan_phase(int wv, const Params& P, LAS unsigned char* lds) {
;     ...
;                 f32x2 yacc = (f32x2){0.f, 0.f};
;                 unsigned sbt = sba, vbt = vba; LAS float* ybt = yb;
;                 RW_LDS_LOAD(A, 0); RW_LDS_WAIT(A);
; #pragma unroll 1
;                 for (int tt = 0; tt < RW_T; tt += 16) { sbt = sba + (unsigned)tt * 1280u; vbt = vba + (unsigned)tt * 32u; ybt = yb + tt * 128;
;                     RW_LDS_LOAD(B, 1); RW_STEP(A, 0); RW_LDS_WAIT(B);
;                     RW_LDS_LOAD(A, 2); RW_STEP(B, 1); RW_LDS_WAIT(A);
;                     RW_LDS_LOAD(B, 3); RW_STEP(A, 2); RW_LDS_WAIT(B);
;                     RW_LDS_LOAD(A, 4); RW_STEP(B, 3); RW_LDS_WAIT(A);
;                     RW_LDS_LOAD(B, 5); RW_STEP(A, 4); RW_LDS_WAIT(B);
;                     RW_LDS_LOAD(A, 6); RW_STEP(B, 5); RW_LDS_WAIT(A);
;                     RW_LDS_LOAD(B, 7); RW_STEP(A, 6); RW_LDS_WAIT(B);
;                     RW_LDS_LOAD(A, 8); RW_STEP(B, 7); RW_LDS_WAIT(A);
;                     RW_LDS_LOAD(B, 9); RW_STEP(A, 8); RW_LDS_WAIT(B);
;                     RW_LDS_LOAD(A, 10); RW_STEP(B, 9); RW_LDS_WAIT(A);
;                     RW_LDS_LOAD(B, 11); RW_STEP(A, 10); RW_LDS_WAIT(B);
;                     RW_LDS_LOAD(A, 12); RW_STEP(B, 11); RW_LDS_WAIT(A);
;                     RW_LDS_LOAD(B, 13); RW_STEP(A, 12); RW_LDS_WAIT(B);
;                     RW_LDS_LOAD(A, 14); RW_STEP(B, 13); RW_LDS_WAIT(A);
;                     RW_LDS_LOAD(B, 15); RW_STEP(A, 14); RW_LDS_WAIT(B);
;                     RW_LDS_LOAD(A, 16); RW_STEP(B, 15); RW_LDS_WAIT(A);
;                 }
;                 yb[(RW_T - 1) * 128] = yacc[0] + yacc[1];
	v_xor_b32_e32 v74, 0xc000, v74
	v_xor_b32_e32 v75, 0xc000, v75
	v_pk_mul_f32 v[46:47], v[58:59], v[46:47] op_sel_hi:[0,1]
	v_pk_fma_f32 v[46:47], v[58:59], v[48:49], v[46:47] op_sel:[1,0,0] op_sel_hi:[1,1,1]
	v_pk_fma_f32 v[46:47], v[60:61], v[76:77], v[46:47] op_sel_hi:[0,1,1]
	v_pk_fma_f32 v[46:47], v[60:61], v[78:79], v[46:47] op_sel:[1,0,0] op_sel_hi:[1,1,1]
	v_pk_fma_f32 v[68:69], v[58:59], v[50:51], v[68:69]
	v_pk_fma_f32 v[70:71], v[60:61], v[52:53], v[70:71]
	v_add_f32_dpp v46, v46, v46 quad_perm:[1,0,3,2] row_mask:0xf bank_mask:0xf bound_ctrl:1
	ds_write2st64_b32 v72, v21, v47 offset0:24 offset1:26
	ds_read_b128 v[0:3], v74
	v_add_f32_dpp v46, v46, v46 quad_perm:[2,3,0,1] row_mask:0xf bank_mask:0xf bound_ctrl:1
	ds_read_b128 v[16:19], v74 offset:256
	ds_read_b128 v[4:7], v74 offset:512
	v_add_f32_dpp v46, v46, v46 row_half_mirror row_mask:0xf bank_mask:0xf bound_ctrl:1
	ds_read_b128 v[12:15], v75
	ds_read_b128 v[8:11], v74 offset:768
	v_add_f32_dpp v46, v46, v46 row_mirror row_mask:0xf bank_mask:0xf bound_ctrl:1
	ds_read_b128 v[20:23], v74 offset:3072
	ds_read_b128 v[36:39], v74 offset:3328
	ds_read_b128 v[24:27], v74 offset:3584
	ds_read_b128 v[32:35], v75 offset:3072
	ds_read_b128 v[28:31], v74 offset:3840
	v_pk_fma_f32 v[58:59], v[54:55], v[46:47], v[68:69] op_sel_hi:[1,0,1]
	v_pk_fma_f32 v[60:61], v[56:57], v[46:47], v[70:71] op_sel_hi:[1,0,1]
	v_pk_mul_f32 v[80:81], v[58:59], v[80:81] op_sel_hi:[0,1]
	v_pk_fma_f32 v[80:81], v[58:59], v[82:83], v[80:81] op_sel:[1,0,0] op_sel_hi:[1,1,1]
	v_pk_fma_f32 v[80:81], v[60:61], v[96:97], v[80:81] op_sel_hi:[0,1,1]
	v_pk_fma_f32 v[80:81], v[60:61], v[98:99], v[80:81] op_sel:[1,0,0] op_sel_hi:[1,1,1]
	v_pk_fma_f32 v[92:93], v[58:59], v[84:85], v[92:93]
	v_pk_fma_f32 v[94:95], v[60:61], v[86:87], v[94:95]
	v_add_f32_dpp v80, v80, v80 quad_perm:[1,0,3,2] row_mask:0xf bank_mask:0xf bound_ctrl:1
	ds_read_b128 v[46:49], v74 offset:6144
	ds_read_b128 v[76:79], v74 offset:6400
	v_add_f32_dpp v80, v80, v80 quad_perm:[2,3,0,1] row_mask:0xf bank_mask:0xf bound_ctrl:1
	ds_read_b128 v[50:53], v74 offset:6656
	ds_read_b128 v[68:71], v75 offset:6144
	v_add_f32_dpp v80, v80, v80 row_half_mirror row_mask:0xf bank_mask:0xf bound_ctrl:1
	ds_read_b128 v[54:57], v74 offset:6912
	s_cmpk_eq_i32 s47, 0x200
	v_add_f32_dpp v80, v80, v80 row_mirror row_mask:0xf bank_mask:0xf bound_ctrl:1
	v_pk_fma_f32 v[58:59], v[88:89], v[80:81], v[92:93] op_sel_hi:[1,0,1]
	v_pk_fma_f32 v[60:61], v[90:91], v[80:81], v[94:95] op_sel_hi:[1,0,1]
	s_cbranch_scc0 .Lscan_chunk
	v_add_u32_e32 v40, 0x1e100, v45
	ds_read_b128 v[84:87], v40
	s_waitcnt lgkmcnt(0)
	v_pk_mul_f32 v[64:65], v[84:85], v[58:59]
	v_pk_fma_f32 v[64:65], v[86:87], v[60:61], v[64:65]
	s_nop 0
	v_add_f32_e32 v64, v64, v65
	ds_write2st64_b32 v72, v81, v64 offset0:28 offset1:30
	s_waitcnt lgkmcnt(0)
	s_barrier
